# 4-workgroup clique barriers (same-XCD, checked at run time) for scores->P(VWo) and SwiGLU->down hand-offs instead of grid-wide barriers
# speedup vs baseline: 1.0088x; 1.0033x over previous
; DEVI unsigned xb_ld(unsigned* p)              { return __hip_atomic_load(p, __ATOMIC_RELAXED, __HIP_MEMORY_SCOPE_AGENT); }
; DEVI unsigned xb_add(unsigned* p, unsigned v) { return __hip_atomic_fetch_add(p, v, __ATOMIC_RELAXED, __HIP_MEMORY_SCOPE_AGENT); }
; #define XB_SPIN(cond, bar) do { unsigned _sp = 0; while (cond) { __builtin_amdgcn_s_sleep(1); \
;     if ((++_sp & 255u) == 0u) { if (xb_ld(&(bar)[XB_TMO])) break; if (_sp > XB_SPIN_CAP) { atomicAdd(&(bar)[XB_TMO], 1u); break; } } } } while (0)
; DEVI void xcd_barrier(const XcdBarrier& b) {
;     asm volatile("s_waitcnt vmcnt(0)" ::: "memory");
;     __syncthreads();
;     if (threadIdx.x == 0) {
;         unsigned* bar = b.bar;
;         __builtin_amdgcn_s_waitcnt(0);
;         unsigned nloc = b.st[0], nx = b.st[1];
;         if (nloc == 0u) { xcd_barrier_complete(bar, b.x, nloc, nx); b.st[0] = nloc; b.st[1] = nx; }
;         const unsigned old = xb_add(&bar[XB_XSUB(b.x)], 1u);
;         const unsigned gen = old / nloc;
;         if (old + 1u == (gen + 1u) * nloc) {
;             __builtin_amdgcn_fence(__ATOMIC_RELEASE, "agent");
;             asm volatile("s_waitcnt vmcnt(0)" ::: "memory");
;             const unsigned og = xb_add(&bar[XB_TOP], 1u);
;             const unsigned tg = og / nx;
;             if (og + 1u == (tg + 1u) * nx) xb_add(&bar[XB_TOPGEN], 1u);
;             else XB_SPIN(xb_ld(&bar[XB_TOPGEN]) == tg, bar);
;             __builtin_amdgcn_fence(__ATOMIC_ACQUIRE, "agent");
;             xb_add(&bar[XB_XGEN(b.x)], 1u);
;             asm volatile("s_waitcnt vmcnt(0)" ::: "memory");
;         } else {
;             XB_SPIN(xb_ld(&bar[XB_XGEN(b.x)]) == gen, bar);
;             __builtin_amdgcn_fence(__ATOMIC_ACQUIRE, "agent");
;             asm volatile("s_waitcnt vmcnt(0)" ::: "memory");
;         }
;     }
;     __syncthreads();
; }
.LBB0_1527:
	s_waitcnt vmcnt(0)
	s_barrier
	s_mov_b64 s[2:3], exec
	v_readlane_b32 s0, v251, 6
	v_readlane_b32 s1, v251, 7
	s_and_b64 s[0:1], s[2:3], s[0:1]
	s_mov_b64 exec, s[0:1]
	s_cbranch_execz .LBB0_1575
	v_mov_b32_e32 v1, 0x26008
	ds_read_b32 v1, v1
	s_bfe_u32 s4, s33, 0x30003
	s_lshl_b32 s4, s4, 5
	s_addk_i32 s4, 0x800
	s_mov_b32 s5, 0
	s_waitcnt lgkmcnt(0)
	v_readfirstlane_b32 s6, v1
	v_lshl_add_u64 v[0:1], v[156:157], 0, s[4:5]
	v_mov_b32_e32 v2, 1
	s_cmp_eq_u32 s6, 0
	s_cbranch_scc1 .Lxq_slow_0
	global_atomic_add v3, v[0:1], v2, off sc0
	s_mov_b32 s7, 0
	s_waitcnt vmcnt(0)
	v_or_b32_e32 v3, 3, v3
	v_add_u32_e32 v3, 1, v3
.Lxq_spin_0:
	global_load_dword v2, v[0:1], off sc1
	s_add_u32 s7, s7, 1
	s_waitcnt vmcnt(0)
	v_sub_u32_e32 v2, v2, v3
	v_cmp_le_i32_e32 vcc, 0, v2
	s_cbranch_vccnz .Lxq_done_0
	s_cmp_gt_u32 s7, 0x8000
	s_cbranch_scc1 .Lxq_done_0
	s_sleep 1
	s_branch .Lxq_spin_0
.Lxq_done_0:
	buffer_inv sc1
	s_waitcnt vmcnt(0)
	s_branch .LBB0_1575

; DEVI unsigned xb_ld(unsigned* p)              { return __hip_atomic_load(p, __ATOMIC_RELAXED, __HIP_MEMORY_SCOPE_AGENT); }
; DEVI unsigned xb_add(unsigned* p, unsigned v) { return __hip_atomic_fetch_add(p, v, __ATOMIC_RELAXED, __HIP_MEMORY_SCOPE_AGENT); }
; #define XB_SPIN(cond, bar) do { unsigned _sp = 0; while (cond) { __builtin_amdgcn_s_sleep(1); \
;     if ((++_sp & 255u) == 0u) { if (xb_ld(&(bar)[XB_TMO])) break; if (_sp > XB_SPIN_CAP) { atomicAdd(&(bar)[XB_TMO], 1u); break; } } } } while (0)
; DEVI void xcd_barrier(const XcdBarrier& b) {
;     asm volatile("s_waitcnt vmcnt(0)" ::: "memory");
;     __syncthreads();
;     if (threadIdx.x == 0) {
;         unsigned* bar = b.bar;
;         __builtin_amdgcn_s_waitcnt(0);
;         unsigned nloc = b.st[0], nx = b.st[1];
;         if (nloc == 0u) { xcd_barrier_complete(bar, b.x, nloc, nx); b.st[0] = nloc; b.st[1] = nx; }
;         const unsigned old = xb_add(&bar[XB_XSUB(b.x)], 1u);
;         const unsigned gen = old / nloc;
;         if (old + 1u == (gen + 1u) * nloc) {
;             __builtin_amdgcn_fence(__ATOMIC_RELEASE, "agent");
;             asm volatile("s_waitcnt vmcnt(0)" ::: "memory");
;             const unsigned og = xb_add(&bar[XB_TOP], 1u);
;             const unsigned tg = og / nx;
;             if (og + 1u == (tg + 1u) * nx) xb_add(&bar[XB_TOPGEN], 1u);
;             else XB_SPIN(xb_ld(&bar[XB_TOPGEN]) == tg, bar);
;             __builtin_amdgcn_fence(__ATOMIC_ACQUIRE, "agent");
;             xb_add(&bar[XB_XGEN(b.x)], 1u);
;             asm volatile("s_waitcnt vmcnt(0)" ::: "memory");
;         } else {
;             XB_SPIN(xb_ld(&bar[XB_XGEN(b.x)]) == gen, bar);
;             __builtin_amdgcn_fence(__ATOMIC_ACQUIRE, "agent");
;             asm volatile("s_waitcnt vmcnt(0)" ::: "memory");
;         }
;     }
;     __syncthreads();
; }
.LBB0_1677:
	s_waitcnt vmcnt(0)
	s_waitcnt lgkmcnt(0)
	s_barrier
	s_mov_b64 s[2:3], exec
	v_readlane_b32 s0, v251, 6
	v_readlane_b32 s1, v251, 7
	s_and_b64 s[0:1], s[2:3], s[0:1]
	s_mov_b64 exec, s[0:1]
	s_cbranch_execz .LBB0_1725
	v_mov_b32_e32 v1, 0x26008
	ds_read_b32 v1, v1
	s_bfe_u32 s4, s33, 0x30003
	s_lshl_b32 s4, s4, 5
	s_addk_i32 s4, 0x800
	s_mov_b32 s5, 0
	s_waitcnt lgkmcnt(0)
	v_readfirstlane_b32 s6, v1
	v_lshl_add_u64 v[0:1], v[156:157], 0, s[4:5]
	v_mov_b32_e32 v2, 1
	s_cmp_eq_u32 s6, 0
	s_cbranch_scc1 .Lxq_slow_1
	global_atomic_add v3, v[0:1], v2, off sc0
	s_mov_b32 s7, 0
	s_waitcnt vmcnt(0)
	v_or_b32_e32 v3, 3, v3
	v_add_u32_e32 v3, 1, v3
